# P3 LayerNorm: next row prefetched through LDS-DMA while the current row is normalised; all per-row parameter loads issued before the prefetch
# speedup vs baseline: 1.0200x; 1.0009x over previous
; __device__ __forceinline__ float* xrow(const Frame& F, int m) { return m < ML ? (float*)(F.out + (size_t)m * D) : WSP(float, WS_XC) + (size_t)(m - ML) * D; }
;     const int gw = F.bid * NWAVES + F.wave, NGW = F.G * NWAVES;
;     bf16* HB = WSP(bf16, WS_HB);
;     for (int m = gw; m < nrows; m += NGW) {
;         float* xr = xrow(F, m);
;         const float* xs = (m < ML) ? (src_l ? src_l + (size_t)m * D : xr) : (src_c ? src_c + (size_t)(m - ML) * D : xr);
;         f32x4 v[8];
; #pragma unroll
;         for (int j = 0; j < 8; ++j) v[j] = ((const f32x4*)xs)[F.lane + 64 * j];
;     ...
;         if (MODH) {
;             float s = 0.f;
; #pragma unroll
;             for (int j = 0; j < 8; ++j) s += (v[j].x + v[j].y) + (v[j].z + v[j].w);
.LBB0_403:
	s_or_b64 exec, exec, s[0:1]
	s_mov_b32 s7, s95
	s_mov_b32 s13, s92
	s_mov_b32 s18, s93
	s_mov_b32 s14, s50
	s_waitcnt lgkmcnt(0)
	s_barrier
	v_mbcnt_lo_u32_b32 v0, -1, 0
	v_mbcnt_hi_u32_b32 v0, -1, v0
	s_lshl_b32 s6, s18, 3
	s_add_i32 s6, s6, s7
	s_mov_b64 s[0:1], s[88:89]
	s_mov_b64 s[4:5], s[90:91]
	s_mov_b64 s[2:3], s[86:87]
	s_cmpk_gt_i32 s6, 0x47ff
	s_cbranch_scc1 .LBB0_427
	s_load_dwordx2 s[8:9], s[2:3], 0x10
	s_load_dwordx4 s[20:23], s[2:3], 0x30
	s_cmp_eq_u32 s14, 0
	s_mul_i32 s3, s14, 0xa2000
	s_mul_hi_i32 s2, s14, 0xa2000
	s_waitcnt lgkmcnt(0)
	s_cselect_b32 s9, s9, 0
	s_cselect_b32 s8, s8, 0
	s_add_u32 s3, s4, s3
	s_addc_u32 s2, s5, s2
	s_add_u32 s10, s3, 0x100000
	s_addc_u32 s11, s2, 0
	s_lshl_b32 s12, s13, 3
	s_mul_hi_i32 s15, s14, 0x6000
	s_mulk_i32 s14, 0x6000
	s_add_u32 s2, s20, s14
	s_addc_u32 s3, s21, s15
	s_add_u32 s20, s22, s14
	v_ashrrev_i32_e32 v1, 31, v0
	s_addc_u32 s21, s23, s15
	v_lshlrev_b64 v[4:5], 4, v[0:1]
	s_cmp_eq_u64 s[8:9], 0
	v_lshl_add_u64 v[60:61], s[2:3], 0, v[4:5]
	v_lshl_add_u64 v[62:63], s[20:21], 0, v[4:5]
	v_lshl_add_u64 v[4:5], s[10:11], 0, v[4:5]
	s_mov_b64 s[20:21], 0x94000
	s_cselect_b64 s[14:15], -1, 0
	s_cmp_lg_u64 s[4:5], 0
	v_lshl_add_u64 v[80:81], v[4:5], 0, s[20:21]
	s_mov_b64 s[20:21], 0x95000
	s_cselect_b64 s[16:17], -1, 0
	s_add_u32 s28, s4, 0x400000
	v_lshl_add_u64 v[82:83], v[4:5], 0, s[20:21]
	s_mov_b64 s[20:21], 0x95400
	s_addc_u32 s29, s5, 0
	v_lshl_add_u64 v[84:85], v[4:5], 0, s[20:21]
	s_mov_b64 s[20:21], 0x95800
	v_lshl_add_u64 v[86:87], v[4:5], 0, s[20:21]
	s_mov_b64 s[20:21], 0x95c00
	s_add_u32 s30, s4, 0x300000
	v_lshl_add_u64 v[88:89], v[4:5], 0, s[20:21]
	s_addc_u32 s31, s5, 0
	v_lshlrev_b64 v[4:5], 3, v[0:1]
	s_lshl_b32 s18, s18, 4
	s_lshl_b32 s7, s7, 1
	v_lshl_add_u64 v[6:7], s[4:5], 0, v[4:5]
	s_mov_b64 s[20:21], 0x31400000
	s_add_i32 s18, s18, s7
	s_ashr_i32 s7, s6, 31
	s_mov_b64 s[2:3], 0x1000
	v_lshl_add_u64 v[90:91], v[6:7], 0, s[20:21]
	s_lshl_b32 s33, s13, 4
	s_lshl_b64 s[20:21], s[6:7], 12
	v_lshl_add_u64 v[64:65], v[60:61], 0, s[2:3]
	v_lshl_add_u64 v[66:67], v[62:63], 0, s[2:3]
	s_mov_b64 s[2:3], 0x1400
	s_add_u32 s4, s4, s20
	v_lshl_add_u64 v[68:69], v[60:61], 0, s[2:3]
	v_lshl_add_u64 v[70:71], v[62:63], 0, s[2:3]
	s_mov_b64 s[2:3], 0x1800
	s_addc_u32 s5, s5, s21
	v_add_u32_e32 v52, 0x100, v0
	v_add_u32_e32 v54, 0x140, v0
	v_add_u32_e32 v56, 0x180, v0
	v_add_u32_e32 v58, 0x1c0, v0
	v_lshl_add_u64 v[72:73], v[60:61], 0, s[2:3]
	v_lshl_add_u64 v[74:75], v[62:63], 0, s[2:3]
	s_mov_b64 s[2:3], 0x1c00
	v_lshl_add_u64 v[4:5], s[4:5], 0, v[4:5]
	s_mov_b64 s[4:5], 0x1400000
	s_ashr_i32 s13, s12, 31
	v_ashrrev_i32_e32 v53, 31, v52
	v_ashrrev_i32_e32 v55, 31, v54
	v_ashrrev_i32_e32 v57, 31, v56
	v_ashrrev_i32_e32 v59, 31, v58
	v_lshl_add_u64 v[76:77], v[60:61], 0, s[2:3]
	v_lshl_add_u64 v[78:79], v[62:63], 0, s[2:3]
	v_cmp_eq_u32_e64 s[2:3], 0, v0
	v_lshl_add_u64 v[92:93], v[4:5], 0, s[4:5]
	s_lshl_b64 s[20:21], s[12:13], 12
	s_lshl_b32 s4, s95, 13
	v_lshl_add_u32 v250, v0, 4, s4
	s_mov_b32 s4, s6
	s_cmpk_lt_i32 s4, 0x4000
	s_cselect_b32 s5, 0, 0x4000
	s_sub_i32 s4, s4, s5
	v_mov_b32_e32 v252, s4
	v_mov_b32_e32 v253, 0
	v_lshlrev_b64 v[252:253], 13, v[252:253]
	v_lshl_add_u64 v[252:253], v[0:1], 4, v[252:253]
	s_cmp_eq_u32 s5, 0
	s_cselect_b64 vcc, -1, 0
	s_cselect_b32 s4, s0, s28
	s_cselect_b32 s5, s1, s29
	s_or_b64 vcc, vcc, s[14:15]
	s_cselect_b32 s4, s4, s8
	s_cselect_b32 s5, s5, s9
	v_lshl_add_u64 v[252:253], v[252:253], 0, s[4:5]
	v_add_co_u32_e32 v246, vcc, 0x1000, v252
	s_nop 1
	v_addc_co_u32_e32 v247, vcc, 0, v253, vcc
	s_lshl_b32 s4, s95, 13
	s_mov_b32 m0, s4
	s_nop 0
	global_load_lds_dwordx4 v[252:253], off
	global_load_lds_dwordx4 v[252:253], off offset:1024
	global_load_lds_dwordx4 v[252:253], off offset:2048
	global_load_lds_dwordx4 v[252:253], off offset:3072
	s_add_i32 s4, s4, 0x1000
	s_mov_b32 m0, s4
	s_nop 0
	global_load_lds_dwordx4 v[246:247], off
	global_load_lds_dwordx4 v[246:247], off offset:1024
	global_load_lds_dwordx4 v[246:247], off offset:2048
	global_load_lds_dwordx4 v[246:247], off offset:3072
	s_waitcnt vmcnt(0)
	s_branch .LBB0_406
.LBB0_405:
	s_or_b64 exec, exec, s[4:5]
	v_mov_b32_e32 v4, v32
	v_mov_b32_e32 v5, v26
	v_mov_b32_e32 v18, v33
	v_mov_b32_e32 v19, v27
	v_pk_add_f32 v[4:5], v[4:5], v[18:19]
	v_mov_b32_e32 v18, v34
	v_mov_b32_e32 v19, v28
	v_mov_b32_e32 v24, v35
	v_mov_b32_e32 v25, v29
	v_pk_add_f32 v[18:19], v[18:19], v[24:25]
	v_mov_b32_e32 v24, v36
	v_pk_add_f32 v[4:5], v[4:5], v[18:19]
	v_mov_b32_e32 v18, v37
	v_mov_b32_e32 v19, v38
	v_mov_b32_e32 v25, v39
	v_pk_add_f32 v[18:19], v[18:19], v[24:25]
	v_add_f32_e32 v3, 0, v4
	v_pk_add_f32 v[18:19], v[18:19], v[18:19] op_sel:[0,1] op_sel_hi:[1,0]
	v_add_f32_e32 v4, v3, v5
	v_add_f32_e32 v24, v20, v21
	v_add_f32_e32 v30, v22, v23
	v_mov_b32_e32 v5, v14
	v_mov_b32_e32 v19, v15
	v_mov_b32_e32 v25, v16
	v_mov_b32_e32 v31, v17
	v_pk_add_f32 v[4:5], v[4:5], v[18:19]
	v_pk_add_f32 v[18:19], v[24:25], v[30:31]
	v_mov_b32_e32 v24, v40
	v_pk_add_f32 v[4:5], v[4:5], v[18:19]
	v_mov_b32_e32 v18, v41
	v_mov_b32_e32 v19, v42
	v_mov_b32_e32 v25, v43
	v_pk_add_f32 v[18:19], v[18:19], v[24:25]
	v_pk_add_f32 v[4:5], v[4:5], v[4:5] op_sel:[0,1] op_sel_hi:[1,0]
	v_pk_add_f32 v[18:19], v[18:19], v[18:19] op_sel:[0,1] op_sel_hi:[1,0]
	v_add_f32_e32 v24, v6, v7
	v_add_f32_e32 v30, v8, v9
	v_mov_b32_e32 v5, v10
	v_mov_b32_e32 v19, v11
	v_mov_b32_e32 v25, v12
	v_mov_b32_e32 v31, v13
	v_pk_add_f32 v[4:5], v[4:5], v[18:19]
	v_pk_add_f32 v[18:19], v[24:25], v[30:31]
	s_nop 0
	v_pk_add_f32 v[4:5], v[4:5], v[18:19]
	s_nop 0
	v_add_f32_e32 v3, v4, v5
	v_mov_b32_e32 v4, v2
	s_nop 0
;     ...
;             for (int j = 0; j < 8; ++j) s += (v[j].x + v[j].y) + (v[j].z + v[j].w);
;             const float mean = wave_sum(s) * (1.f / D); float s2 = 0.f;
; #pragma unroll
;             for (int j = 0; j < 8; ++j) { v[j] = v[j] - mean; s2 += (v[j].x * v[j].x + v[j].y * v[j].y) + (v[j].z * v[j].z + v[j].w * v[j].w); }
;             const float rstd = 1.f / sqrtf(wave_sum(s2) * (1.f / D) + LN_EPS);
;             const int bsel = m < ML ? (m >> 11) : 8;
;             const f32x4* shp = (const f32x4*)(mods_l + (size_t)bsel * 18432 + kshift * 2048);
;             const f32x4* scp = (const f32x4*)(mods_l + (size_t)bsel * 18432 + kscale * 2048);
;             v2u* hp = (v2u*)(HB + (size_t)m * D);
	v_add_f32_dpp v3, v3, v3 quad_perm:[1,0,3,2] row_mask:0xf bank_mask:0xf bound_ctrl:1
	s_nop 1
	v_add_f32_dpp v3, v3, v3 quad_perm:[2,3,0,1] row_mask:0xf bank_mask:0xf bound_ctrl:1
	s_nop 1
	v_add_f32_dpp v3, v3, v3 row_half_mirror row_mask:0xf bank_mask:0xf bound_ctrl:1
	s_nop 1
	v_add_f32_dpp v3, v3, v3 row_mirror row_mask:0xf bank_mask:0xf bound_ctrl:1
	s_nop 1
	v_mov_b32_dpp v4, v3 row_bcast:15 row_mask:0xa bank_mask:0xf
	v_add_f32_e32 v3, v3, v4
	v_mov_b32_e32 v4, v2
	s_nop 1
	v_mov_b32_dpp v4, v3 row_bcast:31 row_mask:0xc bank_mask:0xf
	v_add_f32_e32 v3, v3, v4
	s_nop 0
	v_readlane_b32 s4, v3, 63
	s_nop 1
	v_fmac_f32_e32 v35, s4, v224
	v_fmac_f32_e32 v33, s4, v224
	v_fma_f32 v34, s4, v224, v34
	v_fma_f32 v32, s4, v224, v32
	v_mul_f32_e32 v3, v33, v33
	v_mul_f32_e32 v4, v35, v35
	v_fmac_f32_e32 v3, v32, v32
	v_fmac_f32_e32 v4, v34, v34
	v_fmac_f32_e32 v29, s4, v224
	v_fmac_f32_e32 v27, s4, v224
	v_add_f32_e32 v3, v3, v4
	v_fma_f32 v28, s4, v224, v28
	v_fma_f32 v26, s4, v224, v26
	v_mul_f32_e32 v4, v27, v27
	v_mul_f32_e32 v5, v29, v29
	v_fmac_f32_e32 v4, v26, v26
	v_fmac_f32_e32 v5, v28, v28
	v_add_f32_e32 v4, v4, v5
	v_fmac_f32_e32 v39, s4, v224
	v_fmac_f32_e32 v37, s4, v224
	v_add_f32_e32 v3, v3, v4
	v_fma_f32 v38, s4, v224, v38
	v_fma_f32 v36, s4, v224, v36
	v_mul_f32_e32 v4, v37, v37
	v_mul_f32_e32 v5, v39, v39
	v_fmac_f32_e32 v4, v36, v36
	v_fmac_f32_e32 v5, v38, v38
	v_add_f32_e32 v4, v4, v5
	v_fmac_f32_e32 v23, s4, v224
	v_fmac_f32_e32 v21, s4, v224
	v_add_f32_e32 v3, v4, v3
	v_fma_f32 v22, s4, v224, v22
	v_fma_f32 v20, s4, v224, v20
	v_mul_f32_e32 v4, v21, v21
	v_mul_f32_e32 v5, v23, v23
	v_fmac_f32_e32 v4, v20, v20
	v_fmac_f32_e32 v5, v22, v22
	v_add_f32_e32 v4, v4, v5
	v_fmac_f32_e32 v17, s4, v224
	v_fmac_f32_e32 v15, s4, v224
	v_add_f32_e32 v3, v4, v3
	v_fma_f32 v16, s4, v224, v16
	v_fma_f32 v14, s4, v224, v14
	v_mul_f32_e32 v4, v15, v15
	v_mul_f32_e32 v5, v17, v17
	v_fmac_f32_e32 v4, v14, v14
	v_fmac_f32_e32 v5, v16, v16
	v_add_f32_e32 v4, v4, v5
	v_fmac_f32_e32 v43, s4, v224
	v_fmac_f32_e32 v41, s4, v224
	v_add_f32_e32 v3, v4, v3
	v_fma_f32 v42, s4, v224, v42
	v_fma_f32 v40, s4, v224, v40
	v_mul_f32_e32 v4, v41, v41
	v_mul_f32_e32 v5, v43, v43
	v_fmac_f32_e32 v4, v40, v40
	v_fmac_f32_e32 v5, v42, v42
	v_add_f32_e32 v4, v4, v5
	v_fmac_f32_e32 v9, s4, v224
	v_fmac_f32_e32 v7, s4, v224
	v_add_f32_e32 v3, v4, v3
	v_fma_f32 v8, s4, v224, v8
	v_fma_f32 v6, s4, v224, v6
	v_mul_f32_e32 v4, v7, v7
	v_mul_f32_e32 v5, v9, v9
	v_fmac_f32_e32 v4, v6, v6
	v_fmac_f32_e32 v5, v8, v8
	v_add_f32_e32 v4, v4, v5
	v_fmac_f32_e32 v13, s4, v224
	v_fmac_f32_e32 v11, s4, v224
	v_add_f32_e32 v3, v4, v3
	v_fma_f32 v12, s4, v224, v12
	v_fma_f32 v10, s4, v224, v10
	v_mul_f32_e32 v4, v11, v11
	v_mul_f32_e32 v5, v13, v13
	v_fmac_f32_e32 v4, v10, v10
	v_fmac_f32_e32 v5, v12, v12
	v_add_f32_e32 v4, v4, v5
	v_add_f32_e32 v3, v4, v3
	v_mov_b32_e32 v4, v2
	s_nop 0
	v_add_f32_dpp v3, v3, v3 quad_perm:[1,0,3,2] row_mask:0xf bank_mask:0xf bound_ctrl:1
	s_nop 1
	v_add_f32_dpp v3, v3, v3 quad_perm:[2,3,0,1] row_mask:0xf bank_mask:0xf bound_ctrl:1
	s_nop 1
	v_add_f32_dpp v3, v3, v3 row_half_mirror row_mask:0xf bank_mask:0xf bound_ctrl:1
	s_nop 1
	v_add_f32_dpp v3, v3, v3 row_mirror row_mask:0xf bank_mask:0xf bound_ctrl:1
	s_nop 1
	v_mov_b32_dpp v4, v3 row_bcast:15 row_mask:0xa bank_mask:0xf
	v_add_f32_e32 v3, v3, v4
	v_mov_b32_e32 v4, v2
	s_nop 1
	v_mov_b32_dpp v4, v3 row_bcast:31 row_mask:0xc bank_mask:0xf
	v_add_f32_e32 v3, v3, v4
	s_nop 0
	v_readlane_b32 s4, v3, 63
	s_nop 1
	v_fma_f32 v3, s4, v226, v225
	v_cmp_gt_f32_e32 vcc, s73, v3
	v_mul_f32_e32 v4, 0x4f800000, v3
	s_nop 0
	v_cndmask_b32_e32 v3, v3, v4, vcc
	v_sqrt_f32_e32 v4, v3
	s_nop 0
	v_add_u32_e32 v5, -1, v4
	v_fma_f32 v18, -v5, v4, v3
	v_cmp_ge_f32_e64 s[4:5], 0, v18
	v_add_u32_e32 v18, 1, v4
	s_nop 0
	v_cndmask_b32_e64 v5, v4, v5, s[4:5]
	v_fma_f32 v4, -v18, v4, v3
	v_cmp_lt_f32_e64 s[4:5], 0, v4
	s_nop 1
	v_cndmask_b32_e64 v4, v5, v18, s[4:5]
	v_mul_f32_e32 v5, 0x37800000, v4
	v_cndmask_b32_e32 v4, v4, v5, vcc
	v_cmp_class_f32_e32 vcc, v3, v227
	s_nop 1
	v_cndmask_b32_e32 v3, v4, v3, vcc
	v_div_scale_f32 v4, s[4:5], v3, v3, 1.0
	v_rcp_f32_e32 v5, v4
	s_min_i32 s4, s6, 0x4000
	s_ashr_i32 s4, s4, 11
	s_mul_hi_i32 s5, s4, 0x12000
	v_fma_f32 v18, -v4, v5, 1.0
	v_fmac_f32_e32 v5, v18, v5
	v_div_scale_f32 v18, vcc, 1.0, v3, 1.0
	s_mul_i32 s4, s4, 0x12000
	v_mul_f32_e32 v19, v18, v5
	s_add_u32 s4, s10, s4
	v_fma_f32 v24, -v4, v19, v18
	s_addc_u32 s5, s11, s5
	v_fmac_f32_e32 v19, v24, v5
	v_lshl_add_u64 v[24:25], v[0:1], 4, s[4:5]
	s_mov_b64 s[4:5], 0x6000
	v_fma_f32 v4, -v4, v19, v18
	v_lshl_add_u64 v[30:31], v[24:25], 0, s[4:5]
	s_movk_i32 s4, 0x7000
	v_div_fmas_f32 v4, v4, v5, v19
	v_add_co_u32_e32 v18, vcc, s4, v24
	s_mov_b64 s[4:5], 0x8000
	s_nop 0
	v_addc_co_u32_e32 v19, vcc, 0, v25, vcc
	v_lshl_add_u64 v[94:95], v[24:25], 0, s[4:5]
	v_add_co_u32_e32 v24, vcc, s38, v24
	s_nop 0
	s_nop 0
	v_addc_co_u32_e32 v25, vcc, 0, v25, vcc
	s_nop 0
	v_div_fixup_f32 v4, v4, v3, 1.0
	v_pk_mul_f32 v[32:33], v[32:33], v[4:5] op_sel_hi:[1,0]
	v_pk_mul_f32 v[34:35], v[34:35], v[4:5] op_sel_hi:[1,0]
	v_pk_mul_f32 v[26:27], v[26:27], v[4:5] op_sel_hi:[1,0]
	v_pk_mul_f32 v[28:29], v[28:29], v[4:5] op_sel_hi:[1,0]
	v_pk_mul_f32 v[36:37], v[36:37], v[4:5] op_sel_hi:[1,0]
	v_pk_mul_f32 v[38:39], v[38:39], v[4:5] op_sel_hi:[1,0]
	v_pk_mul_f32 v[20:21], v[20:21], v[4:5] op_sel_hi:[1,0]
	v_pk_mul_f32 v[22:23], v[22:23], v[4:5] op_sel_hi:[1,0]
	v_pk_mul_f32 v[14:15], v[14:15], v[4:5] op_sel_hi:[1,0]
	v_pk_mul_f32 v[16:17], v[16:17], v[4:5] op_sel_hi:[1,0]
	v_pk_mul_f32 v[6:7], v[6:7], v[4:5] op_sel_hi:[1,0]
; __device__ __forceinline__ unsigned pk2(float lo, float hi) { const f32x2 v = {lo, hi}; return __builtin_bit_cast(unsigned, __builtin_convertvector(v, bf2n_t_)); }
; __device__ __forceinline__ float* xrow(const Frame& F, int m) { return m < ML ? (float*)(F.out + (size_t)m * D) : WSP(float, WS_XC) + (size_t)(m - ML) * D; }
;     ...
;     for (int m = gw; m < nrows; m += NGW) {
;         float* xr = xrow(F, m);
;         const float* xs = (m < ML) ? (src_l ? src_l + (size_t)m * D : xr) : (src_c ? src_c + (size_t)(m - ML) * D : xr);
;         f32x4 v[8];
; #pragma unroll
;         for (int j = 0; j < 8; ++j) v[j] = ((const f32x4*)xs)[F.lane + 64 * j];
;     ...
; #pragma unroll
;             for (int j = 0; j < 8; ++j) { const f32x4 sh = shp[F.lane + 64 * j], scl = scp[F.lane + 64 * j]; const f32x4 o = v[j] * rstd * (scl + 1.0f) + sh;
;                 v2u w; w.x = pk2(o.x, o.y); w.y = pk2(o.z, o.w); hp[F.lane + 64 * j] = w; }
	v_pk_mul_f32 v[8:9], v[8:9], v[4:5] op_sel_hi:[1,0]
	v_pk_mul_f32 v[10:11], v[10:11], v[4:5] op_sel_hi:[1,0]
	s_add_u32 s6, s6, s12
	s_addc_u32 s7, s7, s13
	s_add_i32 s18, s18, s33
	s_cmpk_lt_i32 s6, 0x4800
	s_nop 0
	v_pk_add_f32 v[50:51], v[230:231], 1.0 op_sel_hi:[1,0]
	v_pk_add_f32 v[48:49], v[228:229], 1.0 op_sel_hi:[1,0]
	v_pk_fma_f32 v[34:35], v[50:51], v[34:35], v[222:223]
	v_pk_fma_f32 v[32:33], v[48:49], v[32:33], v[220:221]
	s_nop 0
	v_cvt_pk_bf16_f32 v32, v32, v33
	v_cvt_pk_bf16_f32 v33, v34, v35
	global_store_dwordx2 v[92:93], v[32:33], off
	s_nop 0
	s_nop 0
	s_nop 0
	s_nop 0
	v_pk_add_f32 v[46:47], v[110:111], 1.0 op_sel_hi:[1,0]
	v_pk_add_f32 v[44:45], v[108:109], 1.0 op_sel_hi:[1,0]
	v_pk_fma_f32 v[28:29], v[46:47], v[28:29], v[106:107]
	v_pk_fma_f32 v[26:27], v[44:45], v[26:27], v[104:105]
	s_nop 0
	v_cvt_pk_bf16_f32 v26, v26, v27
	v_cvt_pk_bf16_f32 v27, v28, v29
	global_store_dwordx2 v[92:93], v[26:27], off offset:512
	s_nop 0
	s_nop 0
	s_nop 0
	s_nop 0
	v_pk_add_f32 v[34:35], v[118:119], 1.0 op_sel_hi:[1,0]
	v_pk_add_f32 v[32:33], v[116:117], 1.0 op_sel_hi:[1,0]
	v_pk_fma_f32 v[28:29], v[38:39], v[34:35], v[114:115]
	v_pk_fma_f32 v[26:27], v[36:37], v[32:33], v[112:113]
	s_nop 0
	v_cvt_pk_bf16_f32 v26, v26, v27
	v_cvt_pk_bf16_f32 v27, v28, v29
	global_store_dwordx2 v[92:93], v[26:27], off offset:1024
	s_nop 0
	s_nop 0
	s_nop 0
	s_nop 0
	v_pk_add_f32 v[32:33], v[126:127], 1.0 op_sel_hi:[1,0]
	v_pk_add_f32 v[30:31], v[124:125], 1.0 op_sel_hi:[1,0]
	v_pk_fma_f32 v[22:23], v[22:23], v[32:33], v[122:123]
	v_pk_fma_f32 v[20:21], v[20:21], v[30:31], v[120:121]
	s_nop 0
	v_cvt_pk_bf16_f32 v20, v20, v21
	v_cvt_pk_bf16_f32 v21, v22, v23
	global_store_dwordx2 v[92:93], v[20:21], off offset:1536
	s_nop 0
	s_nop 0
	s_nop 0
	s_nop 0
	v_pk_add_f32 v[28:29], v[134:135], 1.0 op_sel_hi:[1,0]
	v_pk_add_f32 v[26:27], v[132:133], 1.0 op_sel_hi:[1,0]
	v_pk_fma_f32 v[16:17], v[16:17], v[28:29], v[130:131]
	v_pk_fma_f32 v[14:15], v[14:15], v[26:27], v[128:129]
	v_pk_mul_f32 v[26:27], v[40:41], v[4:5] op_sel_hi:[1,0]
	v_cvt_pk_bf16_f32 v14, v14, v15
	v_cvt_pk_bf16_f32 v15, v16, v17
	global_store_dwordx2 v[92:93], v[14:15], off offset:2048
	s_nop 0
	s_nop 0
	s_nop 0
	v_pk_mul_f32 v[28:29], v[42:43], v[4:5] op_sel_hi:[1,0]
	v_pk_mul_f32 v[4:5], v[12:13], v[4:5] op_sel_hi:[1,0]
	s_nop 0
	v_pk_add_f32 v[22:23], v[142:143], 1.0 op_sel_hi:[1,0]
	v_pk_add_f32 v[20:21], v[140:141], 1.0 op_sel_hi:[1,0]
	v_pk_fma_f32 v[16:17], v[28:29], v[22:23], v[138:139]
	v_pk_fma_f32 v[14:15], v[26:27], v[20:21], v[136:137]
	s_nop 0
	v_cvt_pk_bf16_f32 v14, v14, v15
	v_cvt_pk_bf16_f32 v15, v16, v17
	global_store_dwordx2 v[92:93], v[14:15], off offset:2560
	s_nop 0
	s_nop 0
	s_nop 0
	s_nop 0
	v_pk_add_f32 v[22:23], v[150:151], 1.0 op_sel_hi:[1,0]
	v_pk_add_f32 v[20:21], v[148:149], 1.0 op_sel_hi:[1,0]
	v_pk_fma_f32 v[8:9], v[8:9], v[22:23], v[146:147]
	v_pk_fma_f32 v[6:7], v[6:7], v[20:21], v[144:145]
	s_nop 0
	v_cvt_pk_bf16_f32 v6, v6, v7
	v_cvt_pk_bf16_f32 v7, v8, v9
	global_store_dwordx2 v[92:93], v[6:7], off offset:3072
	s_nop 0
	s_nop 0
	s_nop 0
	s_nop 0
	v_pk_add_f32 v[12:13], v[158:159], 1.0 op_sel_hi:[1,0]
	v_pk_add_f32 v[14:15], v[156:157], 1.0 op_sel_hi:[1,0]
	v_pk_fma_f32 v[4:5], v[4:5], v[12:13], v[154:155]
	v_pk_fma_f32 v[6:7], v[10:11], v[14:15], v[152:153]
	s_nop 0
	v_cvt_pk_bf16_f32 v6, v6, v7
	v_cvt_pk_bf16_f32 v7, v4, v5
	global_store_dwordx2 v[92:93], v[6:7], off offset:3584
	v_lshl_add_u64 v[92:93], v[92:93], 0, s[20:21]
	s_cbranch_scc0 .LBB0_427
.LBB0_406:
	s_add_i32 s66, s6, 0xffffc000
	s_cmpk_lt_i32 s6, 0x4000
	s_cselect_b64 s[22:23], -1, 0
	s_and_b64 s[4:5], s[22:23], exec
	s_cselect_b32 s5, s7, 0
	s_cselect_b32 s4, s6, s66
	s_cselect_b32 s19, s1, s29
	s_cselect_b32 s24, s0, s28
	s_lshl_b64 s[4:5], s[4:5], 13
	s_add_u32 s24, s24, s4
	s_addc_u32 s25, s19, s5
	s_or_b64 s[4:5], s[14:15], s[22:23]
	s_lshl_b64 s[26:27], s[66:67], 13
	s_add_u32 s19, s8, s26
	s_addc_u32 s26, s9, s27
	s_and_b64 s[4:5], s[4:5], exec
	s_cselect_b32 s4, s25, s26
	s_cselect_b32 s5, s24, s19
	v_mov_b32_e32 v4, s5
	v_mov_b32_e32 v5, s4
	v_lshl_add_u64 v[4:5], v[0:1], 4, v[4:5]
	s_waitcnt vmcnt(8)
	ds_read_b128 v[28:31], v250
	ds_read_b128 v[32:35], v250 offset:1024
	ds_read_b128 v[24:27], v250 offset:2048
	ds_read_b128 v[20:23], v250 offset:3072
	v_add_co_u32_e32 v4, vcc, 0x1000, v4
	s_cmpk_gt_i32 s6, 0x3fff
	s_nop 0
	v_addc_co_u32_e32 v5, vcc, 0, v5, vcc
	ds_read_b128 v[16:19], v250 offset:4096
	ds_read_b128 v[12:15], v250 offset:5120
	ds_read_b128 v[8:11], v250 offset:6144
	s_nop 0
	ds_read_b128 v[4:7], v250 offset:7168
	s_waitcnt lgkmcnt(0)
	s_cselect_b64 s[26:27], -1, 0
	s_and_b64 s[4:5], s[16:17], s[26:27]
	s_andn2_b64 vcc, exec, s[4:5]
	s_cbranch_vccnz .LBB0_408
;     ...
;         if (POST && part != nullptr && m >= ML) {
;             const v2u* pp = (const v2u*)(part + (size_t)(m - ML) * D);
; #pragma unroll
;             for (int j = 0; j < 8; ++j) { const int o = F.lane + 64 * j; const v2u p0 = pp[o], p1 = pp[o + (size_t)MC * D / 4], p2 = pp[o + 2 * ((size_t)MC * D / 4)], p3 = pp[o + 3 * ((size_t)MC * D / 4)];
;                 const f32x4 ps = ((f32x4){bflo(p0.x), bfhi(p0.x), bflo(p0.y), bfhi(p0.y)} + (f32x4){bflo(p1.x), bfhi(p1.x), bflo(p1.y), bfhi(p1.y)}) + ((f32x4){bflo(p2.x), bfhi(p2.x), bflo(p2.y), bfhi(p2.y)} + (f32x4){bflo(p3.x), bfhi(p3.x), bflo(p3.y), bfhi(p3.y)});
;                 v[j] = v[j] * ALPHA + ((const f32x4*)pmod)[o] * pcoef * ps; }
	s_lshl_b64 s[4:5], s[66:67], 12
	v_lshl_add_u64 v[46:47], v[90:91], 0, s[4:5]
	v_add_co_u32_e32 v44, vcc, 0x800000, v46
	global_load_dwordx2 v[36:37], v[46:47], off
	s_nop 0
	v_addc_co_u32_e32 v45, vcc, 0, v47, vcc
	v_add_co_u32_e32 v42, vcc, 0x1000000, v46
	global_load_dwordx2 v[38:39], v[44:45], off
	s_nop 0
	v_addc_co_u32_e32 v43, vcc, 0, v47, vcc
	v_add_co_u32_e32 v40, vcc, 0x1800000, v46
	global_load_dwordx2 v[48:49], v[42:43], off
	s_nop 0
	v_addc_co_u32_e32 v41, vcc, 0, v47, vcc
	global_load_dwordx2 v[50:51], v[40:41], off
	global_load_dwordx4 v[104:107], v[80:81], off
	global_load_dwordx2 v[136:137], v[46:47], off offset:512
	global_load_dwordx2 v[138:139], v[44:45], off offset:512
	global_load_dwordx2 v[140:141], v[42:43], off offset:512
	global_load_dwordx2 v[142:143], v[40:41], off offset:512
	global_load_dwordx4 v[108:111], v[80:81], off offset:1024
	global_load_dwordx2 v[144:145], v[46:47], off offset:1024
	global_load_dwordx2 v[146:147], v[44:45], off offset:1024
	global_load_dwordx2 v[148:149], v[42:43], off offset:1024
	global_load_dwordx2 v[150:151], v[40:41], off offset:1024
	global_load_dwordx4 v[112:115], v[80:81], off offset:2048
	global_load_dwordx2 v[152:153], v[46:47], off offset:1536
	global_load_dwordx2 v[154:155], v[44:45], off offset:1536
	global_load_dwordx2 v[156:157], v[42:43], off offset:1536
	global_load_dwordx2 v[158:159], v[40:41], off offset:1536
	global_load_dwordx4 v[116:119], v[80:81], off offset:3072
	global_load_dwordx2 v[160:161], v[46:47], off offset:2048
	global_load_dwordx2 v[162:163], v[44:45], off offset:2048
	global_load_dwordx2 v[164:165], v[42:43], off offset:2048
	global_load_dwordx2 v[166:167], v[40:41], off offset:2048
	global_load_dwordx4 v[120:123], v[82:83], off
	global_load_dwordx2 v[168:169], v[46:47], off offset:2560
	global_load_dwordx2 v[170:171], v[44:45], off offset:2560
	global_load_dwordx2 v[172:173], v[42:43], off offset:2560
	global_load_dwordx2 v[174:175], v[40:41], off offset:2560
	global_load_dwordx4 v[124:127], v[84:85], off
	global_load_dwordx2 v[176:177], v[46:47], off offset:3072
	global_load_dwordx2 v[178:179], v[44:45], off offset:3072
	global_load_dwordx2 v[180:181], v[42:43], off offset:3072
	global_load_dwordx2 v[182:183], v[40:41], off offset:3072
	global_load_dwordx4 v[128:131], v[86:87], off
	global_load_dwordx2 v[184:185], v[46:47], off offset:3584
	global_load_dwordx2 v[186:187], v[44:45], off offset:3584
	global_load_dwordx2 v[188:189], v[42:43], off offset:3584
	global_load_dwordx2 v[190:191], v[40:41], off offset:3584
	global_load_dwordx4 v[132:135], v[88:89], off
	s_mov_b32 s4, 0x3fb504f3
	s_waitcnt vmcnt(36)
	v_lshlrev_b32_e32 v94, 16, v36
	v_and_b32_e32 v95, 0xffff0000, v36
	v_lshlrev_b32_e32 v36, 16, v37
	v_and_b32_e32 v37, 0xffff0000, v37
	v_lshlrev_b32_e32 v96, 16, v38
	v_and_b32_e32 v97, 0xffff0000, v38
	v_lshlrev_b32_e32 v38, 16, v39
	v_and_b32_e32 v39, 0xffff0000, v39
	v_pk_add_f32 v[94:95], v[94:95], v[96:97]
	v_pk_add_f32 v[36:37], v[36:37], v[38:39]
	v_lshlrev_b32_e32 v38, 16, v48
	v_and_b32_e32 v39, 0xffff0000, v48
	v_lshlrev_b32_e32 v48, 16, v49
	v_and_b32_e32 v49, 0xffff0000, v49
	v_lshlrev_b32_e32 v96, 16, v50
	v_and_b32_e32 v97, 0xffff0000, v50
	v_lshlrev_b32_e32 v50, 16, v51
	v_and_b32_e32 v51, 0xffff0000, v51
	v_pk_add_f32 v[38:39], v[38:39], v[96:97]
	v_pk_add_f32 v[48:49], v[48:49], v[50:51]
	v_pk_add_f32 v[50:51], v[94:95], v[38:39]
	v_pk_add_f32 v[48:49], v[36:37], v[48:49]
	s_nop 0
	s_waitcnt vmcnt(35)
	v_pk_mul_f32 v[38:39], v[106:107], 0.5 op_sel_hi:[1,0]
	v_pk_mul_f32 v[36:37], v[104:105], 0.5 op_sel_hi:[1,0]
	v_pk_mul_f32 v[38:39], v[38:39], v[48:49]
	v_pk_mul_f32 v[36:37], v[36:37], v[50:51]
	v_pk_fma_f32 v[30:31], v[30:31], s[4:5], v[38:39] op_sel_hi:[1,0,1]
	v_pk_fma_f32 v[28:29], v[28:29], s[4:5], v[36:37] op_sel_hi:[1,0,1]
	s_nop 0
	s_nop 0
	s_nop 0
	s_nop 0
	s_waitcnt vmcnt(34)
	v_lshlrev_b32_e32 v94, 16, v136
	v_and_b32_e32 v95, 0xffff0000, v136
	v_lshlrev_b32_e32 v36, 16, v137
	v_and_b32_e32 v37, 0xffff0000, v137
	s_waitcnt vmcnt(33)
	v_lshlrev_b32_e32 v96, 16, v138
	v_and_b32_e32 v97, 0xffff0000, v138
	v_lshlrev_b32_e32 v38, 16, v139
	v_and_b32_e32 v39, 0xffff0000, v139
	v_pk_add_f32 v[94:95], v[94:95], v[96:97]
	v_pk_add_f32 v[36:37], v[36:37], v[38:39]
	s_waitcnt vmcnt(32)
	v_lshlrev_b32_e32 v38, 16, v140
	v_and_b32_e32 v39, 0xffff0000, v140
	v_lshlrev_b32_e32 v48, 16, v141
	v_and_b32_e32 v49, 0xffff0000, v141
	s_waitcnt vmcnt(31)
	v_lshlrev_b32_e32 v96, 16, v142
	v_and_b32_e32 v97, 0xffff0000, v142
	v_lshlrev_b32_e32 v50, 16, v143
	v_and_b32_e32 v51, 0xffff0000, v143
	v_pk_add_f32 v[38:39], v[38:39], v[96:97]
	v_pk_add_f32 v[48:49], v[48:49], v[50:51]
	v_pk_add_f32 v[50:51], v[94:95], v[38:39]
	v_pk_add_f32 v[48:49], v[36:37], v[48:49]
	s_nop 0
	s_waitcnt vmcnt(30)
	v_pk_mul_f32 v[38:39], v[110:111], 0.5 op_sel_hi:[1,0]
	v_pk_mul_f32 v[36:37], v[108:109], 0.5 op_sel_hi:[1,0]
	s_nop 0
	v_pk_mul_f32 v[50:51], v[36:37], v[50:51]
	v_pk_mul_f32 v[36:37], v[38:39], v[48:49]
	v_pk_fma_f32 v[38:39], v[32:33], s[4:5], v[50:51] op_sel_hi:[1,0,1]
	v_pk_fma_f32 v[36:37], v[34:35], s[4:5], v[36:37] op_sel_hi:[1,0,1]
	s_nop 0
	s_nop 0
	s_nop 0
	s_nop 0
	s_waitcnt vmcnt(29)
	v_lshlrev_b32_e32 v94, 16, v144
	v_and_b32_e32 v95, 0xffff0000, v144
	v_lshlrev_b32_e32 v32, 16, v145
	v_and_b32_e32 v33, 0xffff0000, v145
	s_waitcnt vmcnt(28)
	v_lshlrev_b32_e32 v96, 16, v146
	v_and_b32_e32 v97, 0xffff0000, v146
	v_lshlrev_b32_e32 v34, 16, v147
	v_and_b32_e32 v35, 0xffff0000, v147
	v_pk_add_f32 v[94:95], v[94:95], v[96:97]
	v_pk_add_f32 v[32:33], v[32:33], v[34:35]
	s_waitcnt vmcnt(27)
;     ...
;         if (POST && part != nullptr && m >= ML) {
;             const v2u* pp = (const v2u*)(part + (size_t)(m - ML) * D);
; #pragma unroll
;             for (int j = 0; j < 8; ++j) { const int o = F.lane + 64 * j; const v2u p0 = pp[o], p1 = pp[o + (size_t)MC * D / 4], p2 = pp[o + 2 * ((size_t)MC * D / 4)], p3 = pp[o + 3 * ((size_t)MC * D / 4)];
;                 const f32x4 ps = ((f32x4){bflo(p0.x), bfhi(p0.x), bflo(p0.y), bfhi(p0.y)} + (f32x4){bflo(p1.x), bfhi(p1.x), bflo(p1.y), bfhi(p1.y)}) + ((f32x4){bflo(p2.x), bfhi(p2.x), bflo(p2.y), bfhi(p2.y)} + (f32x4){bflo(p3.x), bfhi(p3.x), bflo(p3.y), bfhi(p3.y)});
;                 v[j] = v[j] * ALPHA + ((const f32x4*)pmod)[o] * pcoef * ps; }
	v_lshlrev_b32_e32 v34, 16, v148
	v_and_b32_e32 v35, 0xffff0000, v148
	v_lshlrev_b32_e32 v48, 16, v149
	v_and_b32_e32 v49, 0xffff0000, v149
	s_waitcnt vmcnt(26)
	v_lshlrev_b32_e32 v96, 16, v150
	v_and_b32_e32 v97, 0xffff0000, v150
	v_lshlrev_b32_e32 v50, 16, v151
	v_and_b32_e32 v51, 0xffff0000, v151
	v_pk_add_f32 v[34:35], v[34:35], v[96:97]
	v_pk_add_f32 v[48:49], v[48:49], v[50:51]
	v_pk_add_f32 v[50:51], v[94:95], v[34:35]
	v_pk_add_f32 v[48:49], v[32:33], v[48:49]
	s_nop 0
	s_waitcnt vmcnt(25)
	v_pk_mul_f32 v[34:35], v[114:115], 0.5 op_sel_hi:[1,0]
	v_pk_mul_f32 v[32:33], v[112:113], 0.5 op_sel_hi:[1,0]
	v_pk_mul_f32 v[34:35], v[34:35], v[48:49]
	v_pk_mul_f32 v[32:33], v[32:33], v[50:51]
	v_pk_fma_f32 v[26:27], v[26:27], s[4:5], v[34:35] op_sel_hi:[1,0,1]
	v_pk_fma_f32 v[24:25], v[24:25], s[4:5], v[32:33] op_sel_hi:[1,0,1]
	s_nop 0
	s_nop 0
	s_nop 0
	s_nop 0
	s_waitcnt vmcnt(24)
	v_lshlrev_b32_e32 v94, 16, v152
	v_and_b32_e32 v95, 0xffff0000, v152
	v_lshlrev_b32_e32 v32, 16, v153
	v_and_b32_e32 v33, 0xffff0000, v153
	s_waitcnt vmcnt(23)
	v_lshlrev_b32_e32 v96, 16, v154
	v_and_b32_e32 v97, 0xffff0000, v154
	v_lshlrev_b32_e32 v34, 16, v155
	v_and_b32_e32 v35, 0xffff0000, v155
	v_pk_add_f32 v[94:95], v[94:95], v[96:97]
	v_pk_add_f32 v[32:33], v[32:33], v[34:35]
	s_waitcnt vmcnt(22)
	v_lshlrev_b32_e32 v34, 16, v156
	v_and_b32_e32 v35, 0xffff0000, v156
	v_lshlrev_b32_e32 v48, 16, v157
	v_and_b32_e32 v49, 0xffff0000, v157
	s_waitcnt vmcnt(21)
	v_lshlrev_b32_e32 v96, 16, v158
	v_and_b32_e32 v97, 0xffff0000, v158
	v_lshlrev_b32_e32 v50, 16, v159
	v_and_b32_e32 v51, 0xffff0000, v159
	v_pk_add_f32 v[34:35], v[34:35], v[96:97]
	v_pk_add_f32 v[48:49], v[48:49], v[50:51]
	v_pk_add_f32 v[50:51], v[94:95], v[34:35]
	v_pk_add_f32 v[48:49], v[32:33], v[48:49]
	s_nop 0
	s_waitcnt vmcnt(20)
	v_pk_mul_f32 v[34:35], v[118:119], 0.5 op_sel_hi:[1,0]
	v_pk_mul_f32 v[32:33], v[116:117], 0.5 op_sel_hi:[1,0]
	v_pk_mul_f32 v[34:35], v[34:35], v[48:49]
	v_pk_mul_f32 v[32:33], v[32:33], v[50:51]
	v_pk_fma_f32 v[22:23], v[22:23], s[4:5], v[34:35] op_sel_hi:[1,0,1]
	v_pk_fma_f32 v[20:21], v[20:21], s[4:5], v[32:33] op_sel_hi:[1,0,1]
	s_nop 0
	s_nop 0
	s_nop 0
	s_nop 0
	s_waitcnt vmcnt(19)
	v_lshlrev_b32_e32 v94, 16, v160
	v_and_b32_e32 v95, 0xffff0000, v160
	v_lshlrev_b32_e32 v32, 16, v161
	v_and_b32_e32 v33, 0xffff0000, v161
	s_waitcnt vmcnt(18)
	v_lshlrev_b32_e32 v96, 16, v162
	v_and_b32_e32 v97, 0xffff0000, v162
	v_lshlrev_b32_e32 v34, 16, v163
	v_and_b32_e32 v35, 0xffff0000, v163
	v_pk_add_f32 v[94:95], v[94:95], v[96:97]
	v_pk_add_f32 v[32:33], v[32:33], v[34:35]
	s_waitcnt vmcnt(17)
	v_lshlrev_b32_e32 v34, 16, v164
	v_and_b32_e32 v35, 0xffff0000, v164
	v_lshlrev_b32_e32 v48, 16, v165
	v_and_b32_e32 v49, 0xffff0000, v165
	s_waitcnt vmcnt(16)
	v_lshlrev_b32_e32 v96, 16, v166
	v_and_b32_e32 v97, 0xffff0000, v166
	v_lshlrev_b32_e32 v50, 16, v167
	v_and_b32_e32 v51, 0xffff0000, v167
	v_pk_add_f32 v[34:35], v[34:35], v[96:97]
	v_pk_add_f32 v[48:49], v[48:49], v[50:51]
	v_pk_add_f32 v[50:51], v[94:95], v[34:35]
	v_pk_add_f32 v[48:49], v[32:33], v[48:49]
	s_nop 0
	s_waitcnt vmcnt(15)
	v_pk_mul_f32 v[34:35], v[122:123], 0.5 op_sel_hi:[1,0]
	v_pk_mul_f32 v[32:33], v[120:121], 0.5 op_sel_hi:[1,0]
	v_pk_mul_f32 v[34:35], v[34:35], v[48:49]
	v_pk_mul_f32 v[32:33], v[32:33], v[50:51]
	v_pk_fma_f32 v[18:19], v[18:19], s[4:5], v[34:35] op_sel_hi:[1,0,1]
	v_pk_fma_f32 v[16:17], v[16:17], s[4:5], v[32:33] op_sel_hi:[1,0,1]
	s_nop 0
	s_nop 0
	s_nop 0
	s_nop 0
	s_waitcnt vmcnt(14)
	v_lshlrev_b32_e32 v94, 16, v168
	v_and_b32_e32 v95, 0xffff0000, v168
	v_lshlrev_b32_e32 v32, 16, v169
	v_and_b32_e32 v33, 0xffff0000, v169
	s_waitcnt vmcnt(13)
	v_lshlrev_b32_e32 v96, 16, v170
	v_and_b32_e32 v97, 0xffff0000, v170
	v_lshlrev_b32_e32 v34, 16, v171
	v_and_b32_e32 v35, 0xffff0000, v171
	v_pk_add_f32 v[94:95], v[94:95], v[96:97]
	v_pk_add_f32 v[32:33], v[32:33], v[34:35]
	s_waitcnt vmcnt(12)
	v_lshlrev_b32_e32 v34, 16, v172
	v_and_b32_e32 v35, 0xffff0000, v172
	v_lshlrev_b32_e32 v48, 16, v173
	v_and_b32_e32 v49, 0xffff0000, v173
	s_waitcnt vmcnt(11)
	v_lshlrev_b32_e32 v96, 16, v174
	v_and_b32_e32 v97, 0xffff0000, v174
	v_lshlrev_b32_e32 v50, 16, v175
	v_and_b32_e32 v51, 0xffff0000, v175
	v_pk_add_f32 v[34:35], v[34:35], v[96:97]
	v_pk_add_f32 v[48:49], v[48:49], v[50:51]
	v_pk_add_f32 v[50:51], v[94:95], v[34:35]
	v_pk_add_f32 v[48:49], v[32:33], v[48:49]
	s_nop 0
	s_waitcnt vmcnt(10)
	v_pk_mul_f32 v[34:35], v[126:127], 0.5 op_sel_hi:[1,0]
	v_pk_mul_f32 v[32:33], v[124:125], 0.5 op_sel_hi:[1,0]
	v_pk_mul_f32 v[34:35], v[34:35], v[48:49]
	v_pk_mul_f32 v[32:33], v[32:33], v[50:51]
	v_pk_fma_f32 v[14:15], v[14:15], s[4:5], v[34:35] op_sel_hi:[1,0,1]
	v_pk_fma_f32 v[12:13], v[12:13], s[4:5], v[32:33] op_sel_hi:[1,0,1]
	s_nop 0
	s_nop 0
	s_nop 0
	s_nop 0
	s_waitcnt vmcnt(9)
	v_lshlrev_b32_e32 v94, 16, v176
	v_and_b32_e32 v95, 0xffff0000, v176
	v_lshlrev_b32_e32 v32, 16, v177
	v_and_b32_e32 v33, 0xffff0000, v177
	s_waitcnt vmcnt(8)
	v_lshlrev_b32_e32 v96, 16, v178
	v_and_b32_e32 v97, 0xffff0000, v178
	v_lshlrev_b32_e32 v34, 16, v179
	v_and_b32_e32 v35, 0xffff0000, v179
	v_pk_add_f32 v[94:95], v[94:95], v[96:97]
	v_pk_add_f32 v[32:33], v[32:33], v[34:35]
	s_waitcnt vmcnt(7)
	v_lshlrev_b32_e32 v34, 16, v180
	v_and_b32_e32 v35, 0xffff0000, v180
	v_lshlrev_b32_e32 v48, 16, v181
	v_and_b32_e32 v49, 0xffff0000, v181
	s_waitcnt vmcnt(6)
	v_lshlrev_b32_e32 v96, 16, v182
	v_and_b32_e32 v97, 0xffff0000, v182
	v_lshlrev_b32_e32 v50, 16, v183
	v_and_b32_e32 v51, 0xffff0000, v183
	v_pk_add_f32 v[34:35], v[34:35], v[96:97]
	v_pk_add_f32 v[48:49], v[48:49], v[50:51]
	v_pk_add_f32 v[50:51], v[94:95], v[34:35]
	v_pk_add_f32 v[48:49], v[32:33], v[48:49]
	s_nop 0
	s_waitcnt vmcnt(5)
;     ...
;         if (POST && part != nullptr && m >= ML) {
;             const v2u* pp = (const v2u*)(part + (size_t)(m - ML) * D);
; #pragma unroll
;             for (int j = 0; j < 8; ++j) { const int o = F.lane + 64 * j; const v2u p0 = pp[o], p1 = pp[o + (size_t)MC * D / 4], p2 = pp[o + 2 * ((size_t)MC * D / 4)], p3 = pp[o + 3 * ((size_t)MC * D / 4)];
;                 const f32x4 ps = ((f32x4){bflo(p0.x), bfhi(p0.x), bflo(p0.y), bfhi(p0.y)} + (f32x4){bflo(p1.x), bfhi(p1.x), bflo(p1.y), bfhi(p1.y)}) + ((f32x4){bflo(p2.x), bfhi(p2.x), bflo(p2.y), bfhi(p2.y)} + (f32x4){bflo(p3.x), bfhi(p3.x), bflo(p3.y), bfhi(p3.y)});
;                 v[j] = v[j] * ALPHA + ((const f32x4*)pmod)[o] * pcoef * ps; }
;         }
;         if (POST) {
;             float s = 0.f;
; #pragma unroll
;             for (int j = 0; j < 8; ++j) s += (v[j].x + v[j].y) + (v[j].z + v[j].w);
;             const float mean = wave_sum(s) * (1.f / D); float s2 = 0.f;
; #pragma unroll
;             for (int j = 0; j < 8; ++j) { v[j] = v[j] - mean; s2 += (v[j].x * v[j].x + v[j].y * v[j].y) + (v[j].z * v[j].z + v[j].w * v[j].w); }
;             const float rstd = 1.f / sqrtf(wave_sum(s2) * (1.f / D) + LN_EPS);
; #pragma unroll
;             for (int j = 0; j < 8; ++j) { const f32x4 gg = ((const f32x4*)g)[F.lane + 64 * j], bb = ((const f32x4*)b)[F.lane + 64 * j]; v[j] = v[j] * rstd * gg + bb; if (WX || m >= ML) ((f32x4*)xr)[F.lane + 64 * j] = v[j]; }
;             if (!WX && m < ML && F.lane == 0) *(v2f*)(WSP(float, WS_STATS) + 2 * m) = (v2f){mean, rstd};
;         }
;         if (MODH) {
;             float s = 0.f;
; #pragma unroll
;             for (int j = 0; j < 8; ++j) s += (v[j].x + v[j].y) + (v[j].z + v[j].w);
;             const float mean = wave_sum(s) * (1.f / D); float s2 = 0.f;
; #pragma unroll
;             for (int j = 0; j < 8; ++j) { v[j] = v[j] - mean; s2 += (v[j].x * v[j].x + v[j].y * v[j].y) + (v[j].z * v[j].z + v[j].w * v[j].w); }
;             const float rstd = 1.f / sqrtf(wave_sum(s2) * (1.f / D) + LN_EPS);
;             const int bsel = m < ML ? (m >> 11) : 8;
;             const f32x4* shp = (const f32x4*)(mods_l + (size_t)bsel * 18432 + kshift * 2048);
;             const f32x4* scp = (const f32x4*)(mods_l + (size_t)bsel * 18432 + kscale * 2048);
;             v2u* hp = (v2u*)(HB + (size_t)m * D);
; #pragma unroll
	v_pk_mul_f32 v[34:35], v[130:131], 0.5 op_sel_hi:[1,0]
	v_pk_mul_f32 v[32:33], v[128:129], 0.5 op_sel_hi:[1,0]
	v_pk_mul_f32 v[34:35], v[34:35], v[48:49]
	v_pk_mul_f32 v[32:33], v[32:33], v[50:51]
	v_pk_fma_f32 v[10:11], v[10:11], s[4:5], v[34:35] op_sel_hi:[1,0,1]
	v_pk_fma_f32 v[8:9], v[8:9], s[4:5], v[32:33] op_sel_hi:[1,0,1]
	s_nop 0
	s_nop 0
	s_nop 0
	s_nop 0
	s_nop 0
	s_nop 0
	v_mov_b32_e32 v51, v30
	v_mov_b32_e32 v50, v36
	v_mov_b32_e32 v30, v37
	s_waitcnt vmcnt(4)
	v_lshlrev_b32_e32 v44, 16, v184
	v_and_b32_e32 v45, 0xffff0000, v184
	v_lshlrev_b32_e32 v32, 16, v185
	v_and_b32_e32 v33, 0xffff0000, v185
	s_waitcnt vmcnt(3)
	v_lshlrev_b32_e32 v46, 16, v186
	v_and_b32_e32 v47, 0xffff0000, v186
	v_lshlrev_b32_e32 v34, 16, v187
	v_and_b32_e32 v35, 0xffff0000, v187
	v_pk_add_f32 v[44:45], v[44:45], v[46:47]
	v_pk_add_f32 v[32:33], v[32:33], v[34:35]
	s_waitcnt vmcnt(2)
	v_lshlrev_b32_e32 v34, 16, v188
	v_and_b32_e32 v35, 0xffff0000, v188
	v_lshlrev_b32_e32 v42, 16, v189
	v_and_b32_e32 v43, 0xffff0000, v189
	s_waitcnt vmcnt(1)
	v_lshlrev_b32_e32 v46, 16, v190
	v_and_b32_e32 v47, 0xffff0000, v190
	v_lshlrev_b32_e32 v40, 16, v191
	v_and_b32_e32 v41, 0xffff0000, v191
	v_pk_add_f32 v[34:35], v[34:35], v[46:47]
	v_pk_add_f32 v[40:41], v[42:43], v[40:41]
	v_pk_add_f32 v[42:43], v[44:45], v[34:35]
	v_pk_add_f32 v[40:41], v[32:33], v[40:41]
	s_nop 0
	v_mov_b32_e32 v47, v28
	v_mov_b32_e32 v46, v38
	v_mov_b32_e32 v28, v39
	s_waitcnt vmcnt(0)
	v_pk_mul_f32 v[34:35], v[134:135], 0.5 op_sel_hi:[1,0]
	v_pk_mul_f32 v[32:33], v[132:133], 0.5 op_sel_hi:[1,0]
	v_pk_mul_f32 v[34:35], v[34:35], v[40:41]
	v_pk_mul_f32 v[32:33], v[32:33], v[42:43]
	v_pk_fma_f32 v[6:7], v[6:7], s[4:5], v[34:35] op_sel_hi:[1,0,1]
	v_pk_fma_f32 v[4:5], v[4:5], s[4:5], v[32:33] op_sel_hi:[1,0,1]
	s_branch .LBB0_409
.LBB0_408:
	s_nop 0
	v_mov_b32_e32 v47, v28
	v_mov_b32_e32 v51, v30
	v_mov_b32_e32 v46, v32
	v_mov_b32_e32 v28, v33
	v_mov_b32_e32 v50, v34
	v_mov_b32_e32 v30, v35
.LBB0_409:
	v_pk_add_f32 v[36:37], v[46:47], v[28:29]
	v_pk_add_f32 v[38:39], v[50:51], v[30:31]
	v_mov_b32_e32 v48, v25
	v_pk_add_f32 v[36:37], v[36:37], v[38:39]
	v_mov_b32_e32 v49, v26
	v_mov_b32_e32 v25, v27
	v_add_f32_e32 v3, 0, v37
	v_add_f32_e32 v43, v36, v3
	v_pk_add_f32 v[36:37], v[48:49], v[24:25]
	v_mov_b32_e32 v44, v17
	v_pk_add_f32 v[36:37], v[36:37], v[36:37] op_sel_hi:[0,1]
	v_mov_b32_e32 v42, v19
	v_add_f32_e32 v17, v20, v21
	v_add_f32_e32 v45, v22, v23
	v_mov_b32_e32 v19, v37
	v_mov_b32_e32 v40, v13
	v_mov_b32_e32 v41, v14
	v_mov_b32_e32 v13, v15
	v_pk_add_f32 v[38:39], v[16:17], v[44:45]
	v_pk_add_f32 v[36:37], v[18:19], v[42:43]
	v_mov_b32_e32 v32, v4
	v_pk_add_f32 v[36:37], v[38:39], v[36:37]
	v_pk_add_f32 v[38:39], v[40:41], v[12:13]
	v_pk_add_f32 v[36:37], v[36:37], v[36:37] op_sel_hi:[0,1]
	v_pk_add_f32 v[38:39], v[38:39], v[38:39] op_sel_hi:[0,1]
	v_mov_b32_e32 v34, v5
	v_mov_b32_e32 v14, v6
	v_mov_b32_e32 v26, v7
	v_add_f32_e32 v33, v8, v9
	v_add_f32_e32 v35, v10, v11
	v_mov_b32_e32 v15, v39
	v_mov_b32_e32 v27, v37
	v_pk_add_f32 v[32:33], v[32:33], v[34:35]
	v_pk_add_f32 v[14:15], v[14:15], v[26:27]
	s_nop 0
	v_pk_add_f32 v[14:15], v[32:33], v[14:15]
	global_load_dwordx4 v[32:35], v[60:61], off
	global_load_dwordx4 v[36:39], v[62:63], off
	global_load_dwordx4 v[160:163], v[60:61], off offset:1024
	global_load_dwordx4 v[164:167], v[62:63], off offset:1024
	global_load_dwordx4 v[168:171], v[60:61], off offset:2048
	global_load_dwordx4 v[172:175], v[62:63], off offset:2048
	global_load_dwordx4 v[176:179], v[60:61], off offset:3072
	global_load_dwordx4 v[180:183], v[62:63], off offset:3072
	global_load_dwordx4 v[184:187], v[64:65], off
	global_load_dwordx4 v[188:191], v[66:67], off
	global_load_dwordx4 v[196:199], v[68:69], off
	global_load_dwordx4 v[200:203], v[70:71], off
	global_load_dwordx4 v[204:207], v[72:73], off
	global_load_dwordx4 v[208:211], v[74:75], off
	global_load_dwordx4 v[212:215], v[76:77], off
	global_load_dwordx4 v[216:219], v[78:79], off
	s_min_i32 s4, s6, 0x4000
	s_ashr_i32 s4, s4, 11
	s_mul_hi_i32 s5, s4, 0x12000
	s_mul_i32 s4, s4, 0x12000
	s_add_u32 s4, s10, s4
	s_addc_u32 s5, s11, s5
	s_add_u32 s4, s4, 0x7000
	s_addc_u32 s5, s5, 0
	v_lshl_add_u64 v[244:245], v[0:1], 4, s[4:5]
	s_add_u32 s4, s4, 0x2000
	s_addc_u32 s5, s5, 0
	v_lshl_add_u64 v[240:241], v[0:1], 4, s[4:5]
	global_load_dwordx4 v[220:223], v[244:245], off offset:-4096
	global_load_dwordx4 v[228:231], v[240:241], off offset:-4096
	global_load_dwordx4 v[104:107], v[244:245], off offset:-3072
	global_load_dwordx4 v[108:111], v[240:241], off offset:-3072
	global_load_dwordx4 v[112:115], v[244:245], off offset:-2048
	global_load_dwordx4 v[116:119], v[240:241], off offset:-2048
	global_load_dwordx4 v[120:123], v[244:245], off offset:-1024
	global_load_dwordx4 v[124:127], v[240:241], off offset:-1024
	global_load_dwordx4 v[128:131], v[244:245], off
	global_load_dwordx4 v[132:135], v[240:241], off
	global_load_dwordx4 v[136:139], v[244:245], off offset:1024
	global_load_dwordx4 v[140:143], v[240:241], off offset:1024
	global_load_dwordx4 v[144:147], v[244:245], off offset:2048
	global_load_dwordx4 v[148:151], v[240:241], off offset:2048
	global_load_dwordx4 v[152:155], v[244:245], off offset:3072
	global_load_dwordx4 v[156:159], v[240:241], off offset:3072
	s_add_i32 s4, s6, s12
	s_cmpk_lt_i32 s4, 0x4800
	s_cselect_b32 s4, s4, s6
	s_cmpk_lt_i32 s4, 0x4000
	s_cselect_b32 s5, 0, 0x4000
	s_sub_i32 s4, s4, s5
	v_mov_b32_e32 v252, s4
	v_mov_b32_e32 v253, 0
	v_lshlrev_b64 v[252:253], 13, v[252:253]
	v_lshl_add_u64 v[252:253], v[0:1], 4, v[252:253]
	s_cmp_eq_u32 s5, 0
	s_cselect_b64 vcc, -1, 0
	s_cselect_b32 s4, s0, s28
;     ...
;         if (POST) {
;             float s = 0.f;
; #pragma unroll
;             for (int j = 0; j < 8; ++j) s += (v[j].x + v[j].y) + (v[j].z + v[j].w);
;             const float mean = wave_sum(s) * (1.f / D); float s2 = 0.f;
; #pragma unroll
;             for (int j = 0; j < 8; ++j) { v[j] = v[j] - mean; s2 += (v[j].x * v[j].x + v[j].y * v[j].y) + (v[j].z * v[j].z + v[j].w * v[j].w); }
;             const float rstd = 1.f / sqrtf(wave_sum(s2) * (1.f / D) + LN_EPS);
; #pragma unroll
;             for (int j = 0; j < 8; ++j) { const f32x4 gg = ((const f32x4*)g)[F.lane + 64 * j], bb = ((const f32x4*)b)[F.lane + 64 * j]; v[j] = v[j] * rstd * gg + bb; if (WX || m >= ML) ((f32x4*)xr)[F.lane + 64 * j] = v[j]; }
	s_cselect_b32 s5, s1, s29
	s_or_b64 vcc, vcc, s[14:15]
	s_cselect_b32 s4, s4, s8
	s_cselect_b32 s5, s5, s9
	v_lshl_add_u64 v[252:253], v[252:253], 0, s[4:5]
	v_add_co_u32_e32 v246, vcc, 0x1000, v252
	s_nop 1
	v_addc_co_u32_e32 v247, vcc, 0, v253, vcc
	s_lshl_b32 s4, s95, 13
	s_mov_b32 m0, s4
	s_nop 0
	global_load_lds_dwordx4 v[252:253], off
	global_load_lds_dwordx4 v[252:253], off offset:1024
	global_load_lds_dwordx4 v[252:253], off offset:2048
	global_load_lds_dwordx4 v[252:253], off offset:3072
	s_add_i32 s4, s4, 0x1000
	s_mov_b32 m0, s4
	s_nop 0
	global_load_lds_dwordx4 v[246:247], off
	global_load_lds_dwordx4 v[246:247], off offset:1024
	global_load_lds_dwordx4 v[246:247], off offset:2048
	global_load_lds_dwordx4 v[246:247], off offset:3072
	v_add_f32_e32 v3, v14, v15
	v_mov_b32_e32 v14, v2
	s_nop 0
	v_add_f32_dpp v3, v3, v3 quad_perm:[1,0,3,2] row_mask:0xf bank_mask:0xf bound_ctrl:1
	s_nop 1
	v_add_f32_dpp v3, v3, v3 quad_perm:[2,3,0,1] row_mask:0xf bank_mask:0xf bound_ctrl:1
	s_nop 1
	v_add_f32_dpp v3, v3, v3 row_half_mirror row_mask:0xf bank_mask:0xf bound_ctrl:1
	s_nop 1
	v_add_f32_dpp v3, v3, v3 row_mirror row_mask:0xf bank_mask:0xf bound_ctrl:1
	s_nop 1
	v_mov_b32_dpp v14, v3 row_bcast:15 row_mask:0xa bank_mask:0xf
	v_add_f32_e32 v3, v3, v14
	v_mov_b32_e32 v14, v2
	s_nop 1
	v_mov_b32_dpp v14, v3 row_bcast:31 row_mask:0xc bank_mask:0xf
	v_add_f32_e32 v3, v3, v14
	s_nop 0
	v_readlane_b32 s19, v3, 63
	s_nop 1
	v_fmac_f32_e32 v31, s19, v224
	v_fmac_f32_e32 v29, s19, v224
	v_fmac_f32_e32 v51, s19, v224
	v_fmac_f32_e32 v47, s19, v224
	v_mul_f32_e32 v3, v29, v29
	v_mul_f32_e32 v14, v31, v31
	v_fmac_f32_e32 v3, v47, v47
	v_fmac_f32_e32 v14, v51, v51
	v_fmac_f32_e32 v30, s19, v224
	v_fmac_f32_e32 v28, s19, v224
	v_add_f32_e32 v3, v3, v14
	v_fmac_f32_e32 v50, s19, v224
	v_fmac_f32_e32 v46, s19, v224
	v_mul_f32_e32 v14, v28, v28
	v_mul_f32_e32 v15, v30, v30
	v_fmac_f32_e32 v14, v46, v46
	v_fmac_f32_e32 v15, v50, v50
	v_add_f32_e32 v14, v14, v15
	v_fmac_f32_e32 v25, s19, v224
	v_fmac_f32_e32 v48, s19, v224
	v_add_f32_e32 v3, v3, v14
	v_fmac_f32_e32 v49, s19, v224
	v_fmac_f32_e32 v24, s19, v224
	v_mul_f32_e32 v14, v48, v48
	v_mul_f32_e32 v15, v25, v25
	v_fmac_f32_e32 v14, v24, v24
	v_fmac_f32_e32 v15, v49, v49
	v_add_f32_e32 v14, v14, v15
	v_fmac_f32_e32 v23, s19, v224
	v_fmac_f32_e32 v21, s19, v224
	v_add_f32_e32 v3, v14, v3
	v_fmac_f32_e32 v22, s19, v224
	v_fmac_f32_e32 v20, s19, v224
	v_mul_f32_e32 v14, v21, v21
	v_mul_f32_e32 v15, v23, v23
	v_fmac_f32_e32 v14, v20, v20
	v_fmac_f32_e32 v15, v22, v22
	v_add_f32_e32 v14, v14, v15
	v_fmac_f32_e32 v42, s19, v224
	v_fmac_f32_e32 v44, s19, v224
	v_add_f32_e32 v3, v14, v3
	v_fmac_f32_e32 v18, s19, v224
	v_fmac_f32_e32 v16, s19, v224
	v_mul_f32_e32 v14, v44, v44
	v_mul_f32_e32 v15, v42, v42
	v_fmac_f32_e32 v14, v16, v16
	v_fmac_f32_e32 v15, v18, v18
	v_add_f32_e32 v14, v14, v15
	v_fmac_f32_e32 v13, s19, v224
	v_fmac_f32_e32 v40, s19, v224
	v_add_f32_e32 v3, v14, v3
	v_fmac_f32_e32 v41, s19, v224
	v_fmac_f32_e32 v12, s19, v224
	v_mul_f32_e32 v14, v40, v40
	v_mul_f32_e32 v15, v13, v13
	v_fmac_f32_e32 v14, v12, v12
	v_fmac_f32_e32 v15, v41, v41
	v_add_f32_e32 v14, v14, v15
	v_fmac_f32_e32 v11, s19, v224
	v_fmac_f32_e32 v9, s19, v224
	v_add_f32_e32 v3, v14, v3
	v_fmac_f32_e32 v10, s19, v224
	v_fmac_f32_e32 v8, s19, v224
	v_mul_f32_e32 v14, v9, v9
	v_mul_f32_e32 v15, v11, v11
	v_fma_f32 v95, s19, v224, v7
	v_fma_f32 v5, s19, v224, v5
	v_fmac_f32_e32 v14, v8, v8
	v_fmac_f32_e32 v15, v10, v10
	v_fma_f32 v94, s19, v224, v6
	v_fmac_f32_e32 v4, s19, v224
	v_mul_f32_e32 v6, v5, v5
	v_mul_f32_e32 v7, v95, v95
	v_add_f32_e32 v14, v14, v15
	v_fmac_f32_e32 v6, v4, v4
	v_fmac_f32_e32 v7, v94, v94
	v_add_f32_e32 v3, v14, v3
	v_add_f32_e32 v6, v6, v7
	v_add_f32_e32 v3, v6, v3
	v_mov_b32_e32 v6, v2
	s_nop 0
	v_add_f32_dpp v3, v3, v3 quad_perm:[1,0,3,2] row_mask:0xf bank_mask:0xf bound_ctrl:1
	s_nop 1
	v_add_f32_dpp v3, v3, v3 quad_perm:[2,3,0,1] row_mask:0xf bank_mask:0xf bound_ctrl:1
	s_nop 1
	v_add_f32_dpp v3, v3, v3 row_half_mirror row_mask:0xf bank_mask:0xf bound_ctrl:1
	s_nop 1
	v_add_f32_dpp v3, v3, v3 row_mirror row_mask:0xf bank_mask:0xf bound_ctrl:1
	s_nop 1
	v_mov_b32_dpp v6, v3 row_bcast:15 row_mask:0xa bank_mask:0xf
	v_add_f32_e32 v3, v3, v6
	v_mov_b32_e32 v6, v2
	s_nop 1
	v_mov_b32_dpp v6, v3 row_bcast:31 row_mask:0xc bank_mask:0xf
	v_add_f32_e32 v3, v3, v6
	s_nop 0
	v_readlane_b32 s4, v3, 63
	s_nop 1
	v_fma_f32 v3, s4, v226, v225
	v_cmp_gt_f32_e32 vcc, s73, v3
	v_mul_f32_e32 v6, 0x4f800000, v3
	s_nop 0
	v_cndmask_b32_e32 v3, v3, v6, vcc
	v_sqrt_f32_e32 v6, v3
	s_nop 0
	v_add_u32_e32 v7, -1, v6
	v_fma_f32 v14, -v7, v6, v3
	v_cmp_ge_f32_e64 s[4:5], 0, v14
	v_add_u32_e32 v14, 1, v6
	s_nop 0
	v_cndmask_b32_e64 v7, v6, v7, s[4:5]
	v_fma_f32 v6, -v14, v6, v3
	v_cmp_lt_f32_e64 s[4:5], 0, v6
	s_nop 1
	v_cndmask_b32_e64 v6, v7, v14, s[4:5]
	v_mul_f32_e32 v7, 0x37800000, v6
	v_cndmask_b32_e32 v6, v6, v7, vcc
	v_cmp_class_f32_e32 vcc, v3, v227
	s_nop 1
	v_cndmask_b32_e32 v3, v6, v3, vcc
	v_div_scale_f32 v6, s[4:5], v3, v3, 1.0
	v_rcp_f32_e32 v7, v6
	s_nop 0
	v_fma_f32 v14, -v6, v7, 1.0
	v_fmac_f32_e32 v7, v14, v7
	v_div_scale_f32 v14, vcc, 1.0, v3, 1.0
	v_mul_f32_e32 v15, v14, v7
	v_fma_f32 v17, -v6, v15, v14
	v_fmac_f32_e32 v15, v17, v7
	v_fma_f32 v6, -v6, v15, v14
	v_div_fmas_f32 v6, v6, v7, v15
	v_div_fixup_f32 v96, v6, v3, 1.0
	v_mov_b32_e32 v6, v47
	v_mov_b32_e32 v7, v29
	v_mov_b32_e32 v14, v51
	v_mov_b32_e32 v15, v31
	v_pk_mul_f32 v[6:7], v[6:7], v[96:97] op_sel_hi:[1,0]
	v_pk_mul_f32 v[14:15], v[14:15], v[96:97] op_sel_hi:[1,0]
	v_cndmask_b32_e64 v3, 0, 1, s[26:27]
	s_waitcnt vmcnt(8)
	v_pk_fma_f32 v[34:35], v[34:35], v[14:15], v[38:39]
	v_pk_fma_f32 v[32:33], v[32:33], v[6:7], v[36:37]
	v_cmp_ne_u32_e64 s[4:5], 1, v3
	s_andn2_b64 vcc, exec, s[26:27]
	v_lshl_add_u64 v[6:7], v[0:1], 4, s[24:25]
	s_cbranch_vccnz .LBB0_411
	global_store_dwordx4 v[6:7], v[32:35], off
